# fused-norm row-sum exchange via data-tagged 8-byte granules (sc1 store + sc1 sweep) instead of payload/drain/counter/poll/acquire/barrier/loads
# baseline (speedup 1.0000x reference)
; __device__ __forceinline__ float xadd16(float v) { const unsigned u = __builtin_bit_cast(unsigned, v); const auto r = __builtin_amdgcn_permlane16_swap(u, u, false, false); return __builtin_bit_cast(float, (unsigned)r[0]) + __builtin_bit_cast(float, (unsigned)r[1]); }
; __device__ __forceinline__ float xadd32(float v) { const unsigned u = __builtin_bit_cast(unsigned, v); const auto r = __builtin_amdgcn_permlane32_swap(u, u, false, false); return __builtin_bit_cast(float, (unsigned)r[0]) + __builtin_bit_cast(float, (unsigned)r[1]); }
; #define PG8_WAIT_V(n) asm volatile("s_waitcnt vmcnt(" #n ")" ::: "memory")
; #define PG8_BAR __builtin_amdgcn_s_barrier()
;     __device__ __forceinline__ void fused(f32x4 (&acc)[2][2][4][2], const Unit& u, int wr, int wc, int fr, int fq, LAS unsigned char* lds, int wid, int lane) const {
;     ...
;         for (int ai = 0; ai < 2; ++ai)
; #pragma unroll
;             for (int m = 0; m < 4; ++m) { float sq = 0.f;
; #pragma unroll
;                 for (int bj = 0; bj < 2; ++bj)
; #pragma unroll
;                     for (int n = 0; n < 2; ++n) { const f32x4 x = acc[ai][bj][m][n]; sq += (x[0] * x[0] + x[1] * x[1]) + (x[2] * x[2] + x[3] * x[3]); }
;                 sq = xadd32(xadd16(sq));
;                 if (fq == 0) P[(ai * HALF + wr * 64 + m * 16 + fr) * 4 + wc] = sq; }
; template <class Epi, class Sched>
; __device__ __forceinline__ void gemm_phase(LAS unsigned char* lds, const Gemm g, const Sched& S, const Epi& E) {
;     ...
;     PG8_WAIT_V(0);
;     PG8_BAR;
.LBB0_288:
	v_mul_f32_e32 v2, v131, v131
	v_mul_f32_e32 v3, v133, v133
	v_fmac_f32_e32 v2, v130, v130
	v_fmac_f32_e32 v3, v132, v132
	v_add_f32_e32 v2, v2, v3
	v_mul_f32_e32 v3, v127, v127
	v_mul_f32_e32 v4, v129, v129
	v_fmac_f32_e32 v3, v126, v126
	v_fmac_f32_e32 v4, v128, v128
	v_add_f32_e32 v3, v3, v4
	v_add_f32_e32 v2, v3, v2
	v_mul_f32_e32 v3, v115, v115
	v_mul_f32_e32 v4, v117, v117
	v_fmac_f32_e32 v3, v114, v114
	v_fmac_f32_e32 v4, v116, v116
	v_add_f32_e32 v3, v3, v4
	v_add_f32_e32 v2, v3, v2
	v_mul_f32_e32 v3, v103, v103
	v_mul_f32_e32 v4, v105, v105
	v_fmac_f32_e32 v3, v102, v102
	v_fmac_f32_e32 v4, v104, v104
	v_add_f32_e32 v3, v3, v4
	v_add_f32_e32 v2, v3, v2
	v_mov_b32_e32 v3, v2
	s_nop 1
	v_permlane16_swap_b32_e32 v2, v3
	s_waitcnt vmcnt(0)
	s_lshl_b32 s4, s48, 2
	v_add_f32_e32 v2, v2, v3
	v_and_b32_e32 v156, 63, v143
	s_add_i32 s11, s4, 0
	v_mov_b32_e32 v3, v2
	v_cmp_gt_u32_e64 s[38:39], 16, v156
	s_add_i32 s11, s11, 0x20400
	v_permlane32_swap_b32_e32 v2, v3
	s_barrier
	s_and_saveexec_b64 s[4:5], s[38:39]
	s_lshl_b32 s16, s47, 10
	s_add_i32 s16, s11, s16
	v_add_f32_e32 v2, v2, v3
	v_lshl_add_u32 v3, v142, 4, s16
	ds_write_b32 v3, v2
	s_or_b64 exec, exec, s[4:5]
	v_mul_f32_e32 v2, v123, v123
	v_mul_f32_e32 v3, v125, v125
	v_fmac_f32_e32 v2, v122, v122
	v_fmac_f32_e32 v3, v124, v124
	v_add_f32_e32 v2, v2, v3
	v_mul_f32_e32 v3, v119, v119
	v_mul_f32_e32 v4, v121, v121
	v_fmac_f32_e32 v3, v118, v118
	v_fmac_f32_e32 v4, v120, v120
	v_add_f32_e32 v3, v3, v4
	v_add_f32_e32 v2, v3, v2
	v_mul_f32_e32 v3, v95, v95
	v_mul_f32_e32 v4, v97, v97
	v_fmac_f32_e32 v3, v94, v94
	v_fmac_f32_e32 v4, v96, v96
	v_add_f32_e32 v3, v3, v4
	v_add_f32_e32 v2, v3, v2
	v_mul_f32_e32 v3, v87, v87
	v_mul_f32_e32 v4, v89, v89
	v_fmac_f32_e32 v3, v86, v86
	v_fmac_f32_e32 v4, v88, v88
	v_add_f32_e32 v3, v3, v4
	v_add_f32_e32 v2, v3, v2
	v_mov_b32_e32 v3, v2
	s_nop 1
	v_permlane16_swap_b32_e32 v2, v3
	v_add_f32_e32 v2, v2, v3
	v_mov_b32_e32 v3, v2
	s_nop 1
	v_permlane32_swap_b32_e32 v2, v3
	s_and_saveexec_b64 s[4:5], s[38:39]
	s_lshl_b32 s16, s47, 10
	s_add_i32 s16, s11, s16
	v_add_f32_e32 v2, v2, v3
	v_lshl_add_u32 v3, v142, 4, s16
	ds_write_b32 v3, v2 offset:256
	s_or_b64 exec, exec, s[4:5]
	v_mul_f32_e32 v2, v111, v111
	v_mul_f32_e32 v3, v113, v113
	v_fmac_f32_e32 v2, v110, v110
	v_fmac_f32_e32 v3, v112, v112
	v_add_f32_e32 v2, v2, v3
	v_mul_f32_e32 v3, v107, v107
	v_mul_f32_e32 v4, v109, v109
	v_fmac_f32_e32 v3, v106, v106
	v_fmac_f32_e32 v4, v108, v108
	v_add_f32_e32 v3, v3, v4
	v_add_f32_e32 v2, v3, v2
	v_mul_f32_e32 v3, v83, v83
	v_mul_f32_e32 v4, v85, v85
	v_fmac_f32_e32 v3, v82, v82
	v_fmac_f32_e32 v4, v84, v84
	v_add_f32_e32 v3, v3, v4
	v_add_f32_e32 v2, v3, v2
	v_mul_f32_e32 v3, v79, v79
	v_mul_f32_e32 v4, v81, v81
	v_fmac_f32_e32 v3, v78, v78
	v_fmac_f32_e32 v4, v80, v80
	v_add_f32_e32 v3, v3, v4
	v_add_f32_e32 v2, v3, v2
	v_mov_b32_e32 v3, v2
	s_nop 1
	v_permlane16_swap_b32_e32 v2, v3
	v_add_f32_e32 v2, v2, v3
	v_mov_b32_e32 v3, v2
	s_nop 1
	v_permlane32_swap_b32_e32 v2, v3
	s_and_saveexec_b64 s[4:5], s[38:39]
	s_lshl_b32 s16, s47, 10
	s_add_i32 s16, s11, s16
	v_add_f32_e32 v2, v2, v3
	v_lshl_add_u32 v3, v142, 4, s16
	ds_write_b32 v3, v2 offset:512
	s_or_b64 exec, exec, s[4:5]
	v_mul_f32_e32 v2, v99, v99
	v_mul_f32_e32 v3, v101, v101
	v_fmac_f32_e32 v2, v98, v98
	v_fmac_f32_e32 v3, v100, v100
	v_add_f32_e32 v2, v2, v3
	v_mul_f32_e32 v3, v91, v91
	v_mul_f32_e32 v4, v93, v93
	v_fmac_f32_e32 v3, v90, v90
	v_fmac_f32_e32 v4, v92, v92
	v_add_f32_e32 v3, v3, v4
	v_add_f32_e32 v2, v3, v2
	v_mul_f32_e32 v3, v75, v75
	v_mul_f32_e32 v4, v77, v77
	v_fmac_f32_e32 v3, v74, v74
	v_fmac_f32_e32 v4, v76, v76
	v_add_f32_e32 v3, v3, v4
	v_add_f32_e32 v2, v3, v2
	v_mul_f32_e32 v3, v71, v71
	v_mul_f32_e32 v4, v73, v73
	v_fmac_f32_e32 v3, v70, v70
	v_fmac_f32_e32 v4, v72, v72
	v_add_f32_e32 v3, v3, v4
	v_add_f32_e32 v2, v3, v2
	v_mov_b32_e32 v3, v2
	s_nop 1
	v_permlane16_swap_b32_e32 v2, v3
	v_add_f32_e32 v2, v2, v3
	v_mov_b32_e32 v3, v2
	s_nop 1
	v_permlane32_swap_b32_e32 v2, v3
	s_and_saveexec_b64 s[4:5], s[38:39]
	s_lshl_b32 s16, s47, 10
	s_add_i32 s16, s11, s16
	v_add_f32_e32 v2, v2, v3
	v_lshl_add_u32 v3, v142, 4, s16
	ds_write_b32 v3, v2 offset:768
	s_or_b64 exec, exec, s[4:5]
	v_mul_f32_e32 v2, v67, v67
	v_mul_f32_e32 v3, v69, v69
	v_fmac_f32_e32 v2, v66, v66
	v_fmac_f32_e32 v3, v68, v68
	v_add_f32_e32 v2, v2, v3
	v_mul_f32_e32 v3, v63, v63
	v_mul_f32_e32 v4, v65, v65
	v_fmac_f32_e32 v3, v62, v62
	v_fmac_f32_e32 v4, v64, v64
	v_add_f32_e32 v3, v3, v4
	v_add_f32_e32 v2, v3, v2
	v_mul_f32_e32 v3, v47, v47
	v_mul_f32_e32 v4, v49, v49
	v_fmac_f32_e32 v3, v46, v46
	v_fmac_f32_e32 v4, v48, v48
	v_add_f32_e32 v3, v3, v4
	v_add_f32_e32 v2, v3, v2
	v_mul_f32_e32 v3, v39, v39
	v_mul_f32_e32 v4, v41, v41
	v_fmac_f32_e32 v3, v38, v38
	v_fmac_f32_e32 v4, v40, v40
	v_add_f32_e32 v3, v3, v4
	v_add_f32_e32 v2, v3, v2
	v_mov_b32_e32 v3, v2
	s_nop 1
	v_permlane16_swap_b32_e32 v2, v3
	v_add_f32_e32 v2, v2, v3
	v_mov_b32_e32 v3, v2
	s_nop 1
	v_permlane32_swap_b32_e32 v2, v3
	s_and_saveexec_b64 s[4:5], s[38:39]
	s_lshl_b32 s16, s47, 10
	s_add_i32 s16, s11, s16
	v_add_f32_e32 v2, v2, v3
	v_lshl_add_u32 v3, v142, 4, s16
	ds_write_b32 v3, v2 offset:2048
	s_or_b64 exec, exec, s[4:5]
	v_mul_f32_e32 v2, v59, v59
	v_mul_f32_e32 v3, v61, v61
	v_fmac_f32_e32 v2, v58, v58
	v_fmac_f32_e32 v3, v60, v60
	v_add_f32_e32 v2, v2, v3
	v_mul_f32_e32 v3, v55, v55
	v_mul_f32_e32 v4, v57, v57
	v_fmac_f32_e32 v3, v54, v54
	v_fmac_f32_e32 v4, v56, v56
	v_add_f32_e32 v3, v3, v4
	v_add_f32_e32 v2, v3, v2
	v_mul_f32_e32 v3, v31, v31
	v_mul_f32_e32 v4, v33, v33
	v_fmac_f32_e32 v3, v30, v30
; #define LAS __attribute__((address_space(3)))
; __device__ __forceinline__ float xadd16(float v) { const unsigned u = __builtin_bit_cast(unsigned, v); const auto r = __builtin_amdgcn_permlane16_swap(u, u, false, false); return __builtin_bit_cast(float, (unsigned)r[0]) + __builtin_bit_cast(float, (unsigned)r[1]); }
; __device__ __forceinline__ float xadd32(float v) { const unsigned u = __builtin_bit_cast(unsigned, v); const auto r = __builtin_amdgcn_permlane32_swap(u, u, false, false); return __builtin_bit_cast(float, (unsigned)r[0]) + __builtin_bit_cast(float, (unsigned)r[1]); }
;     __device__ __forceinline__ void fused(f32x4 (&acc)[2][2][4][2], const Unit& u, int wr, int wc, int fr, int fq, LAS unsigned char* lds, int wid, int lane) const {
;     ...
;         for (int ai = 0; ai < 2; ++ai)
; #pragma unroll
;             for (int m = 0; m < 4; ++m) { float sq = 0.f;
; #pragma unroll
;                 for (int bj = 0; bj < 2; ++bj)
; #pragma unroll
;                     for (int n = 0; n < 2; ++n) { const f32x4 x = acc[ai][bj][m][n]; sq += (x[0] * x[0] + x[1] * x[1]) + (x[2] * x[2] + x[3] * x[3]); }
;                 sq = xadd32(xadd16(sq));
;                 if (fq == 0) P[(ai * HALF + wr * 64 + m * 16 + fr) * 4 + wc] = sq; }
;         const unsigned rbase = (unsigned)(u.pm * BM + 16 * wid) * (unsigned)D + (unsigned)(u.pn * BM + 4 * lane);
;         HT H[16], H2[16];
;         asm volatile("s_waitcnt lgkmcnt(0)" ::: "memory"); __builtin_amdgcn_s_barrier(); asm volatile("" ::: "memory");
;     ...
;         for (int rep_ = 0; rep_ < 2; ++rep_) { unsigned* xbuf = rep_ ? this->xbuf : xdummy; unsigned* cnt = rep_ ? this->cnt : this->cnt + 12 * 2048;
;     ...
;         if (tid < 256) { const f32x4 pv = *(const LAS f32x4*)(P + tid * 4); const float t = (pv.x + pv.y) + (pv.z + pv.w);
;             __hip_atomic_store(xbuf + (size_t)(u.pm * BM + tid) * 8 + u.pn, __builtin_bit_cast(unsigned, t), __ATOMIC_RELAXED, __HIP_MEMORY_SCOPE_AGENT); }
	v_fmac_f32_e32 v4, v32, v32
	v_add_f32_e32 v3, v3, v4
	v_add_f32_e32 v2, v3, v2
	v_mul_f32_e32 v3, v23, v23
	v_mul_f32_e32 v4, v25, v25
	v_fmac_f32_e32 v3, v22, v22
	v_fmac_f32_e32 v4, v24, v24
	v_add_f32_e32 v3, v3, v4
	v_add_f32_e32 v2, v3, v2
	v_mov_b32_e32 v3, v2
	s_nop 1
	v_permlane16_swap_b32_e32 v2, v3
	v_add_f32_e32 v2, v2, v3
	v_mov_b32_e32 v3, v2
	s_nop 1
	v_permlane32_swap_b32_e32 v2, v3
	s_and_saveexec_b64 s[4:5], s[38:39]
	s_lshl_b32 s16, s47, 10
	s_add_i32 s16, s11, s16
	v_add_f32_e32 v2, v2, v3
	v_lshl_add_u32 v3, v142, 4, s16
	ds_write_b32 v3, v2 offset:2304
	s_or_b64 exec, exec, s[4:5]
	v_mul_f32_e32 v2, v51, v51
	v_mul_f32_e32 v3, v53, v53
	v_fmac_f32_e32 v2, v50, v50
	v_fmac_f32_e32 v3, v52, v52
	v_add_f32_e32 v2, v2, v3
	v_mul_f32_e32 v3, v43, v43
	v_mul_f32_e32 v4, v45, v45
	v_fmac_f32_e32 v3, v42, v42
	v_fmac_f32_e32 v4, v44, v44
	v_add_f32_e32 v3, v3, v4
	v_add_f32_e32 v2, v3, v2
	v_mul_f32_e32 v3, v19, v19
	v_mul_f32_e32 v4, v21, v21
	v_fmac_f32_e32 v3, v18, v18
	v_fmac_f32_e32 v4, v20, v20
	v_add_f32_e32 v3, v3, v4
	v_add_f32_e32 v2, v3, v2
	v_mul_f32_e32 v3, v15, v15
	v_mul_f32_e32 v4, v17, v17
	v_fmac_f32_e32 v3, v14, v14
	v_fmac_f32_e32 v4, v16, v16
	v_add_f32_e32 v3, v3, v4
	v_add_f32_e32 v2, v3, v2
	v_mov_b32_e32 v3, v2
	s_nop 1
	v_permlane16_swap_b32_e32 v2, v3
	v_add_f32_e32 v2, v2, v3
	v_mov_b32_e32 v3, v2
	s_nop 1
	v_permlane32_swap_b32_e32 v2, v3
	s_and_saveexec_b64 s[4:5], s[38:39]
	s_lshl_b32 s16, s47, 10
	s_add_i32 s16, s11, s16
	v_add_f32_e32 v2, v2, v3
	v_lshl_add_u32 v3, v142, 4, s16
	ds_write_b32 v3, v2 offset:2560
	s_or_b64 exec, exec, s[4:5]
	v_mul_f32_e32 v2, v35, v35
	v_mul_f32_e32 v3, v37, v37
	v_fmac_f32_e32 v2, v34, v34
	v_fmac_f32_e32 v3, v36, v36
	v_add_f32_e32 v2, v2, v3
	v_mul_f32_e32 v3, v27, v27
	v_mul_f32_e32 v4, v29, v29
	v_fmac_f32_e32 v3, v26, v26
	v_fmac_f32_e32 v4, v28, v28
	v_add_f32_e32 v3, v3, v4
	v_add_f32_e32 v2, v3, v2
	v_mul_f32_e32 v3, v11, v11
	v_mul_f32_e32 v4, v13, v13
	v_fmac_f32_e32 v3, v10, v10
	v_fmac_f32_e32 v4, v12, v12
	v_add_f32_e32 v3, v3, v4
	v_add_f32_e32 v2, v3, v2
	v_mul_f32_e32 v3, v7, v7
	v_mul_f32_e32 v4, v9, v9
	v_fmac_f32_e32 v3, v6, v6
	v_fmac_f32_e32 v4, v8, v8
	v_add_f32_e32 v3, v3, v4
	v_add_f32_e32 v2, v3, v2
	v_mov_b32_e32 v3, v2
	s_nop 1
	v_permlane16_swap_b32_e32 v2, v3
	v_add_f32_e32 v2, v2, v3
	v_mov_b32_e32 v3, v2
	s_nop 1
	v_permlane32_swap_b32_e32 v2, v3
	s_and_saveexec_b64 s[4:5], s[38:39]
	s_lshl_b32 s16, s47, 10
	s_add_i32 s11, s11, s16
	v_add_f32_e32 v2, v2, v3
	v_lshl_add_u32 v3, v142, 4, s11
	ds_write_b32 v3, v2 offset:2816
	s_or_b64 exec, exec, s[4:5]
	s_and_b32 s4, s45, 0xffffffc0
	v_or_b32_e32 v2, s4, v156
	s_lshl_b32 s18, s64, 1
	v_readlane_b32 s4, v254, 57
	s_add_i32 s18, s18, s4
	s_lshl_b32 s4, s18, 18
	s_add_u32 s4, s12, s4
	s_addc_u32 s5, s13, 0
	s_waitcnt lgkmcnt(0)
	s_barrier
	s_add_u32 s16, s4, 0xc00000
	s_movk_i32 s4, 0x100
	s_addc_u32 s17, s5, 0
	v_cmp_gt_i32_e64 s[42:43], s4, v2
	s_and_saveexec_b64 s[4:5], s[42:43]
	s_cbranch_execz .LBB0_306
	v_lshl_add_u32 v3, v2, 4, 0
	v_add_u32_e32 v3, 0x20400, v3
	ds_read_b128 v[134:137], v3
	s_ashr_i32 s11, s10, 31
	s_waitcnt lgkmcnt(0)
	v_mov_b32_e32 v139, v136
	v_lshl_add_u32 v136, s46, 8, v2
	v_mov_b32_e32 v138, v135
	v_mov_b32_e32 v135, v137
	v_pk_add_f32 v[134:135], v[138:139], v[134:135]
	v_pk_add_f32 v[134:135], v[134:135], v[134:135] op_sel:[0,1] op_sel_hi:[1,0]
	v_lshlrev_b32_e32 v136, 6, v136
	s_lshl_b32 s100, s10, 3
	s_add_i32 s101, s18, 1
	v_add_u32_e32 v136, s100, v136
	v_add_u32_e32 v136, 0x40000, v136
	v_mov_b32_e32 v135, s101
	global_store_dwordx2 v136, v[134:135], s[12:13] sc1
; #define LAS __attribute__((address_space(3)))
;     __device__ __forceinline__ HT hload(unsigned eoff) const { const u32x2 a = *(const u32x2*)((const char*)hi + eoff * 2u); const u32x2 b = *(const u32x2*)((const char*)lo + eoff * 2u); return (u32x4){a.x, a.y, b.x, b.y}; }
;     __device__ __forceinline__ void fused(f32x4 (&acc)[2][2][4][2], const Unit& u, int wr, int wc, int fr, int fq, LAS unsigned char* lds, int wid, int lane) const {
;     ...
; #pragma unroll
;             for (int m = 0; m < 4; ++m)
; #pragma unroll
;                 for (int bj = 0; bj < 2; ++bj)
; #pragma unroll
;                     for (int n = 0; n < 2; ++n) { const int r = wr * 64 + m * 16 + fr, c16 = 32 * bj + 8 * wc + 4 * n + fq;
;                         *(LAS f32x4*)(lds + r * 1024 + ((c16 ^ (r & 15)) << 4)) = acc[0][bj][m][n]; }
;         asm volatile("s_waitcnt vmcnt(0)" ::: "memory");
;         if (wid < 4 && lane == 0) __hip_atomic_fetch_add(cnt + 64 * u.pm, 1u, __ATOMIC_RELAXED, __HIP_MEMORY_SCOPE_AGENT);
; #pragma unroll
;         for (int j = 0; j < 16; ++j) H[j] = hload(rbase + (unsigned)(j * D));
;         if (wid == 0) {
;             const unsigned long long t0 = __builtin_amdgcn_s_memrealtime();
;             for (;;) {
;                 if ((unsigned)__builtin_amdgcn_readfirstlane((int)__hip_atomic_load(cnt + 64 * u.pm, __ATOMIC_RELAXED, __HIP_MEMORY_SCOPE_AGENT)) >= 32u) break;
;                 if (__builtin_amdgcn_s_memrealtime() - t0 > 2000000ull) { if (lane == 0) __hip_atomic_store(tmo, 1u, __ATOMIC_RELAXED, __HIP_MEMORY_SCOPE_AGENT); break; }
;                 __builtin_amdgcn_s_sleep(2);
;             }
;             __builtin_amdgcn_fence(__ATOMIC_ACQUIRE, "agent");
;         }
;         asm volatile("s_waitcnt vmcnt(0) lgkmcnt(0)" ::: "memory"); __builtin_amdgcn_s_barrier(); asm volatile("" ::: "memory");
;         if (tid < 256) { const f32x4* sl = (const f32x4*)(xbuf + (size_t)(u.pm * BM + tid) * 8);
;             const f32x4 a = sl[0], b = sl[1]; const float t = ((a.x + a.y) + (a.z + a.w)) + ((b.x + b.y) + (b.z + b.w));
;             S[tid] = alpha * __builtin_amdgcn_rsqf(t * (1.0f / 2048.0f) + 1e-6f); }
.LBB0_306:
	s_or_b64 exec, exec, s[4:5]
	s_lshl_b32 s34, s18, 11
	s_lshl_b64 s[4:5], s[34:35], 2
	s_add_u32 s4, s12, s4
	s_addc_u32 s5, s13, s5
	s_add_u32 s11, s4, 0x10000
	s_addc_u32 s23, s5, 0
	v_lshrrev_b32_e32 v3, 4, v156
	s_lshl_b32 s4, s48, 3
	s_lshl_b32 s5, s47, 16
	s_add_i32 s5, s5, 0
	v_or_b32_e32 v134, s4, v3
	v_bitop3_b32 v3, s4, v142, v3 bitop3:0x36
	v_lshl_add_u32 v4, v142, 10, s5
	v_lshlrev_b32_e32 v3, 4, v3
	v_add_u32_e32 v158, v4, v3
	v_bitop3_b32 v3, v134, v142, 4 bitop3:0x36
	v_lshlrev_b32_e32 v3, 4, v3
	v_add_u32_e32 v159, v4, v3
	v_bitop3_b32 v3, v134, v142, 32 bitop3:0x36
	v_lshlrev_b32_e32 v3, 4, v3
	v_add_u32_e32 v160, v4, v3
	v_bitop3_b32 v3, v134, v142, 36 bitop3:0x36
	v_lshlrev_b32_e32 v3, 4, v3
	v_add_u32_e32 v161, v4, v3
	ds_write_b128 v158, v[130:133]
	ds_write_b128 v159, v[126:129]
	ds_write_b128 v160, v[114:117]
	ds_write_b128 v161, v[102:105]
	ds_write_b128 v158, v[122:125] offset:16384
	ds_write_b128 v159, v[118:121] offset:16384
	ds_write_b128 v160, v[94:97] offset:16384
	ds_write_b128 v161, v[86:89] offset:16384
	ds_write_b128 v158, v[110:113] offset:32768
	ds_write_b128 v159, v[106:109] offset:32768
	ds_write_b128 v160, v[82:85] offset:32768
	ds_write_b128 v161, v[78:81] offset:32768
	ds_write_b128 v158, v[98:101] offset:49152
	ds_write_b128 v159, v[90:93] offset:49152
	ds_write_b128 v160, v[74:77] offset:49152
	ds_write_b128 v161, v[70:73] offset:49152
	v_cmp_eq_u32_e64 s[40:41], 0, v156
	s_and_saveexec_b64 s[20:21], s[42:43]
	s_cbranch_execz .Lmy_g1_nosweep
	v_lshl_add_u32 v116, s46, 8, v2
	v_lshlrev_b32_e32 v116, 6, v116
	v_add_u32_e32 v116, 0x40000, v116
	global_load_dwordx4 v[100:103], v116, s[12:13] sc1
	global_load_dwordx4 v[104:107], v116, s[12:13] offset:16 sc1
	global_load_dwordx4 v[108:111], v116, s[12:13] offset:32 sc1
	global_load_dwordx4 v[112:115], v116, s[12:13] offset:48 sc1
.Lmy_g1_nosweep:
	s_or_b64 exec, exec, s[20:21]
	s_lshl_b32 s18, s10, 8
	s_lshl_b32 s4, s46, 19
	s_lshl_b32 s5, s44, 15
	v_lshlrev_b32_e32 v3, 2, v156
	s_add_i32 s4, s4, s5
	v_or_b32_e32 v4, s18, v3
	v_add_u32_e32 v157, s4, v4
	s_add_u32 s4, s12, 0x9000000
	v_lshlrev_b32_e32 v154, 1, v157
	s_addc_u32 s5, s13, 0
	v_add_u32_e32 v4, 0x1000, v154
	v_add_u32_e32 v70, 0x2000, v154
	v_add_u32_e32 v71, 0x3000, v154
	v_add_u32_e32 v72, 0x4000, v154
	global_load_dwordx2 v[152:153], v4, s[4:5]
	global_load_dwordx2 v[150:151], v70, s[4:5]
	global_load_dwordx2 v[148:149], v71, s[4:5]
	global_load_dwordx2 v[146:147], v72, s[4:5]
	v_add_u32_e32 v4, 0x5000, v154
	v_add_u32_e32 v70, 0x6000, v154
	v_add_u32_e32 v71, 0x7000, v154
	v_add_u32_e32 v72, 0x8000, v154
	global_load_dwordx2 v[144:145], v4, s[4:5]
	global_load_dwordx2 v[142:143], v70, s[4:5]
	global_load_dwordx2 v[140:141], v71, s[4:5]
	global_load_dwordx2 v[138:139], v72, s[4:5]
	v_add_u32_e32 v4, 0x9000, v154
	v_add_u32_e32 v70, 0xa000, v154
	v_add_u32_e32 v71, 0xb000, v154
	v_add_u32_e32 v72, 0xc000, v154
	global_load_dwordx2 v[136:137], v4, s[4:5]
	global_load_dwordx2 v[134:135], v70, s[4:5]
	global_load_dwordx2 v[132:133], v71, s[4:5]
	global_load_dwordx2 v[130:131], v72, s[4:5]
	v_add_u32_e32 v4, 0xd000, v154
	v_add_u32_e32 v70, 0xe000, v154
	v_add_u32_e32 v71, 0xf000, v154
	global_load_dwordx2 v[74:75], v154, s[4:5]
	global_load_dwordx2 v[128:129], v4, s[4:5]
	global_load_dwordx2 v[126:127], v70, s[4:5]
	global_load_dwordx2 v[124:125], v71, s[4:5]
	s_lshl_b32 s11, s46, 8
	s_and_saveexec_b64 s[20:21], s[42:43]
	s_cbranch_execz .LBB0_323
	s_waitcnt vmcnt(16)
	s_mov_b32 s22, 0
.Lmy_g1_chk:
	v_xor_b32_e32 v117, s101, v101
	v_xor_b32_e32 v118, s101, v103
	v_xor_b32_e32 v119, s101, v105
	v_or3_b32 v117, v117, v118, v119
	v_xor_b32_e32 v118, s101, v107
	v_xor_b32_e32 v119, s101, v109
	v_or3_b32 v117, v117, v118, v119
	v_xor_b32_e32 v118, s101, v111
	v_xor_b32_e32 v119, s101, v113
	v_or3_b32 v117, v117, v118, v119
	v_xor_b32_e32 v118, s101, v115
	v_or_b32_e32 v117, v117, v118
	v_cmp_ne_u32_e32 vcc, 0, v117
	s_cbranch_vccz .Lmy_g1_ok
	s_add_i32 s22, s22, 1
	s_cmpk_lt_u32 s22, 0x4000
	s_cbranch_scc0 .Lmy_g1_tmo
	s_sleep 1
	global_load_dwordx4 v[100:103], v116, s[12:13] sc1
	global_load_dwordx4 v[104:107], v116, s[12:13] offset:16 sc1
	global_load_dwordx4 v[108:111], v116, s[12:13] offset:32 sc1
	global_load_dwordx4 v[112:115], v116, s[12:13] offset:48 sc1
	s_waitcnt vmcnt(0)
	s_branch .Lmy_g1_chk
.Lmy_g1_tmo:
	global_store_dword v5, v232, s[12:13] sc1
.Lmy_g1_ok:
	v_add_f32_e32 v100, v100, v102
	v_add_f32_e32 v104, v104, v106
	v_add_f32_e32 v108, v108, v110
	v_add_f32_e32 v112, v112, v114
	v_add_f32_e32 v100, v100, v104
	v_add_f32_e32 v108, v108, v112
	v_add_f32_e32 v4, v100, v108
	v_fmamk_f32 v4, v4, 0x3a000000, v1
	v_rsq_f32_e32 v4, v4
	v_lshl_add_u32 v2, v2, 2, 0
	v_add_u32_e32 v2, 0x21400, v2
	v_mul_f32_e32 v4, 0.5, v4
	ds_write_b32 v2, v4

; __device__ __forceinline__ float xadd16(float v) { const unsigned u = __builtin_bit_cast(unsigned, v); const auto r = __builtin_amdgcn_permlane16_swap(u, u, false, false); return __builtin_bit_cast(float, (unsigned)r[0]) + __builtin_bit_cast(float, (unsigned)r[1]); }
; __device__ __forceinline__ float xadd32(float v) { const unsigned u = __builtin_bit_cast(unsigned, v); const auto r = __builtin_amdgcn_permlane32_swap(u, u, false, false); return __builtin_bit_cast(float, (unsigned)r[0]) + __builtin_bit_cast(float, (unsigned)r[1]); }
;     __device__ __forceinline__ void fused(f32x4 (&acc)[2][2][4][2], const Unit& u, int wr, int wc, int fr, int fq, LAS unsigned char* lds, int wid, int lane) const {
;     ...
;         for (int ai = 0; ai < 2; ++ai)
; #pragma unroll
;             for (int m = 0; m < 4; ++m) { float sq = 0.f;
; #pragma unroll
;                 for (int bj = 0; bj < 2; ++bj)
; #pragma unroll
;                     for (int n = 0; n < 2; ++n) { const f32x4 x = acc[ai][bj][m][n]; sq += (x[0] * x[0] + x[1] * x[1]) + (x[2] * x[2] + x[3] * x[3]); }
;                 sq = xadd32(xadd16(sq));
;                 if (fq == 0) P[(ai * HALF + wr * 64 + m * 16 + fr) * 4 + wc] = sq; }
.LBB0_1033:
	v_mul_f32_e32 v2, v131, v131
	v_mul_f32_e32 v3, v133, v133
	v_fmac_f32_e32 v2, v130, v130
	v_fmac_f32_e32 v3, v132, v132
	v_add_f32_e32 v2, v2, v3
	v_mul_f32_e32 v3, v127, v127
	v_mul_f32_e32 v134, v129, v129
	v_fmac_f32_e32 v3, v126, v126
	v_fmac_f32_e32 v134, v128, v128
	v_add_f32_e32 v3, v3, v134
	v_add_f32_e32 v2, v3, v2
	v_mul_f32_e32 v3, v115, v115
	v_mul_f32_e32 v134, v117, v117
	v_fmac_f32_e32 v3, v114, v114
	v_fmac_f32_e32 v134, v116, v116
	v_add_f32_e32 v3, v3, v134
	v_add_f32_e32 v2, v3, v2
	v_mul_f32_e32 v3, v103, v103
	v_mul_f32_e32 v134, v105, v105
	v_fmac_f32_e32 v3, v102, v102
	v_fmac_f32_e32 v134, v104, v104
	v_add_f32_e32 v3, v3, v134
	v_add_f32_e32 v2, v3, v2
	v_mov_b32_e32 v3, v2
	s_nop 1
	v_permlane16_swap_b32_e32 v2, v3
	s_lshl_b32 s5, s54, 2
	v_add_f32_e32 v2, v2, v3
	v_and_b32_e32 v216, 63, v169
	s_add_i32 s5, s5, 0
	v_mov_b32_e32 v3, v2
	v_cmp_gt_u32_e64 s[38:39], 16, v216
	s_add_i32 s5, s5, 0x20400
	v_permlane32_swap_b32_e32 v2, v3
	s_and_saveexec_b64 s[12:13], s[38:39]
	s_lshl_b32 s7, s52, 10
	s_add_i32 s7, s5, s7
	v_add_f32_e32 v2, v2, v3
	v_lshl_add_u32 v3, v168, 4, s7
	ds_write_b32 v3, v2
	s_or_b64 exec, exec, s[12:13]
	v_mul_f32_e32 v2, v123, v123
	v_mul_f32_e32 v3, v125, v125
	v_fmac_f32_e32 v2, v122, v122
	v_fmac_f32_e32 v3, v124, v124
	v_add_f32_e32 v2, v2, v3
	v_mul_f32_e32 v3, v119, v119
	v_mul_f32_e32 v134, v121, v121
	v_fmac_f32_e32 v3, v118, v118
	v_fmac_f32_e32 v134, v120, v120
	v_add_f32_e32 v3, v3, v134
	v_add_f32_e32 v2, v3, v2
	v_mul_f32_e32 v3, v95, v95
	v_mul_f32_e32 v134, v97, v97
	v_fmac_f32_e32 v3, v94, v94
	v_fmac_f32_e32 v134, v96, v96
	v_add_f32_e32 v3, v3, v134
	v_add_f32_e32 v2, v3, v2
	v_mul_f32_e32 v3, v87, v87
	v_mul_f32_e32 v134, v89, v89
	v_fmac_f32_e32 v3, v86, v86
	v_fmac_f32_e32 v134, v88, v88
	v_add_f32_e32 v3, v3, v134
	v_add_f32_e32 v2, v3, v2
	v_mov_b32_e32 v3, v2
	s_nop 1
	v_permlane16_swap_b32_e32 v2, v3
	v_add_f32_e32 v2, v2, v3
	v_mov_b32_e32 v3, v2
	s_nop 1
	v_permlane32_swap_b32_e32 v2, v3
	s_and_saveexec_b64 s[12:13], s[38:39]
	s_lshl_b32 s7, s52, 10
	s_add_i32 s7, s5, s7
	v_add_f32_e32 v2, v2, v3
	v_lshl_add_u32 v3, v168, 4, s7
	ds_write_b32 v3, v2 offset:256
	s_or_b64 exec, exec, s[12:13]
	v_mul_f32_e32 v2, v111, v111
	v_mul_f32_e32 v3, v113, v113
	v_fmac_f32_e32 v2, v110, v110
	v_fmac_f32_e32 v3, v112, v112
	v_add_f32_e32 v2, v2, v3
	v_mul_f32_e32 v3, v107, v107
	v_mul_f32_e32 v134, v109, v109
	v_fmac_f32_e32 v3, v106, v106
	v_fmac_f32_e32 v134, v108, v108
	v_add_f32_e32 v3, v3, v134
	v_add_f32_e32 v2, v3, v2
	v_mul_f32_e32 v3, v83, v83
	v_mul_f32_e32 v134, v85, v85
	v_fmac_f32_e32 v3, v82, v82
	v_fmac_f32_e32 v134, v84, v84
	v_add_f32_e32 v3, v3, v134
	v_add_f32_e32 v2, v3, v2
	v_mul_f32_e32 v3, v79, v79
	v_mul_f32_e32 v134, v81, v81
	v_fmac_f32_e32 v3, v78, v78
	v_fmac_f32_e32 v134, v80, v80
	v_add_f32_e32 v3, v3, v134
	v_add_f32_e32 v2, v3, v2
	v_mov_b32_e32 v3, v2
	s_nop 1
	v_permlane16_swap_b32_e32 v2, v3
	v_add_f32_e32 v2, v2, v3
	v_mov_b32_e32 v3, v2
	s_nop 1
	v_permlane32_swap_b32_e32 v2, v3
	s_and_saveexec_b64 s[12:13], s[38:39]
	s_lshl_b32 s7, s52, 10
	s_add_i32 s7, s5, s7
	v_add_f32_e32 v2, v2, v3
	v_lshl_add_u32 v3, v168, 4, s7
	ds_write_b32 v3, v2 offset:512
	s_or_b64 exec, exec, s[12:13]
	v_mul_f32_e32 v2, v99, v99
	v_mul_f32_e32 v3, v101, v101
	v_fmac_f32_e32 v2, v98, v98
	v_fmac_f32_e32 v3, v100, v100
	v_add_f32_e32 v2, v2, v3
	v_mul_f32_e32 v3, v91, v91
	v_mul_f32_e32 v134, v93, v93
	v_fmac_f32_e32 v3, v90, v90
	v_fmac_f32_e32 v134, v92, v92
	v_add_f32_e32 v3, v3, v134
	v_add_f32_e32 v2, v3, v2
	v_mul_f32_e32 v3, v75, v75
	v_mul_f32_e32 v134, v77, v77
	v_fmac_f32_e32 v3, v74, v74
	v_fmac_f32_e32 v134, v76, v76
	v_add_f32_e32 v3, v3, v134
	v_add_f32_e32 v2, v3, v2
	v_mul_f32_e32 v3, v71, v71
	v_mul_f32_e32 v134, v73, v73
	v_fmac_f32_e32 v3, v70, v70
	v_fmac_f32_e32 v134, v72, v72
	v_add_f32_e32 v3, v3, v134
	v_add_f32_e32 v2, v3, v2
	v_mov_b32_e32 v3, v2
	s_nop 1
	v_permlane16_swap_b32_e32 v2, v3
	v_add_f32_e32 v2, v2, v3
	v_mov_b32_e32 v3, v2
	s_nop 1
	v_permlane32_swap_b32_e32 v2, v3
	s_and_saveexec_b64 s[12:13], s[38:39]
	s_lshl_b32 s7, s52, 10
	s_add_i32 s7, s5, s7
	v_add_f32_e32 v2, v2, v3
	v_lshl_add_u32 v3, v168, 4, s7
	ds_write_b32 v3, v2 offset:768
	s_or_b64 exec, exec, s[12:13]
	v_mul_f32_e32 v2, v67, v67
	v_mul_f32_e32 v3, v69, v69
	v_fmac_f32_e32 v2, v66, v66
	v_fmac_f32_e32 v3, v68, v68
	v_add_f32_e32 v2, v2, v3
	v_mul_f32_e32 v3, v63, v63
	v_mul_f32_e32 v134, v65, v65
	v_fmac_f32_e32 v3, v62, v62
	v_fmac_f32_e32 v134, v64, v64
	v_add_f32_e32 v3, v3, v134
	v_add_f32_e32 v2, v3, v2
	v_mul_f32_e32 v3, v47, v47
	v_mul_f32_e32 v134, v49, v49
	v_fmac_f32_e32 v3, v46, v46
	v_fmac_f32_e32 v134, v48, v48
	v_add_f32_e32 v3, v3, v134
	v_add_f32_e32 v2, v3, v2
	v_mul_f32_e32 v3, v39, v39
	v_mul_f32_e32 v134, v41, v41
	v_fmac_f32_e32 v3, v38, v38
	v_fmac_f32_e32 v134, v40, v40
	v_add_f32_e32 v3, v3, v134
	v_add_f32_e32 v2, v3, v2
	v_mov_b32_e32 v3, v2
	s_nop 1
	v_permlane16_swap_b32_e32 v2, v3
	v_add_f32_e32 v2, v2, v3
	v_mov_b32_e32 v3, v2
	s_nop 1
	v_permlane32_swap_b32_e32 v2, v3
	s_and_saveexec_b64 s[12:13], s[38:39]
	s_lshl_b32 s7, s52, 10
	s_add_i32 s7, s5, s7
	v_add_f32_e32 v2, v2, v3
	v_lshl_add_u32 v3, v168, 4, s7
	ds_write_b32 v3, v2 offset:2048
	s_or_b64 exec, exec, s[12:13]
	v_mul_f32_e32 v2, v59, v59
	v_mul_f32_e32 v3, v61, v61
	v_fmac_f32_e32 v2, v58, v58
	v_fmac_f32_e32 v3, v60, v60
	v_add_f32_e32 v2, v2, v3
	v_mul_f32_e32 v3, v55, v55
	v_mul_f32_e32 v134, v57, v57
	v_fmac_f32_e32 v3, v54, v54
	v_fmac_f32_e32 v134, v56, v56
	v_add_f32_e32 v3, v3, v134
	v_add_f32_e32 v2, v3, v2
	v_mul_f32_e32 v3, v31, v31
; #define LAS __attribute__((address_space(3)))
; __device__ __forceinline__ float xadd16(float v) { const unsigned u = __builtin_bit_cast(unsigned, v); const auto r = __builtin_amdgcn_permlane16_swap(u, u, false, false); return __builtin_bit_cast(float, (unsigned)r[0]) + __builtin_bit_cast(float, (unsigned)r[1]); }
;     __device__ __forceinline__ void fused(f32x4 (&acc)[2][2][4][2], const Unit& u, int wr, int wc, int fr, int fq, LAS unsigned char* lds, int wid, int lane) const {
;     ...
;         for (int ai = 0; ai < 2; ++ai)
; #pragma unroll
;             for (int m = 0; m < 4; ++m) { float sq = 0.f;
; #pragma unroll
;                 for (int bj = 0; bj < 2; ++bj)
; #pragma unroll
;                     for (int n = 0; n < 2; ++n) { const f32x4 x = acc[ai][bj][m][n]; sq += (x[0] * x[0] + x[1] * x[1]) + (x[2] * x[2] + x[3] * x[3]); }
;                 sq = xadd32(xadd16(sq));
;                 if (fq == 0) P[(ai * HALF + wr * 64 + m * 16 + fr) * 4 + wc] = sq; }
;         const unsigned rbase = (unsigned)(u.pm * BM + 16 * wid) * (unsigned)D + (unsigned)(u.pn * BM + 4 * lane);
;         HT H[16], H2[16];
;         asm volatile("s_waitcnt lgkmcnt(0)" ::: "memory"); __builtin_amdgcn_s_barrier(); asm volatile("" ::: "memory");
;     ...
;         for (int rep_ = 0; rep_ < 2; ++rep_) { unsigned* xbuf = rep_ ? this->xbuf : xdummy; unsigned* cnt = rep_ ? this->cnt : this->cnt + 12 * 2048;
;     ...
;         if (tid < 256) { const f32x4 pv = *(const LAS f32x4*)(P + tid * 4); const float t = (pv.x + pv.y) + (pv.z + pv.w);
;             __hip_atomic_store(xbuf + (size_t)(u.pm * BM + tid) * 8 + u.pn, __builtin_bit_cast(unsigned, t), __ATOMIC_RELAXED, __HIP_MEMORY_SCOPE_AGENT); }
; #pragma unroll
;             for (int m = 0; m < 4; ++m)
; #pragma unroll
;                 for (int bj = 0; bj < 2; ++bj)
; #pragma unroll
;                     for (int n = 0; n < 2; ++n) { const int r = wr * 64 + m * 16 + fr, c16 = 32 * bj + 8 * wc + 4 * n + fq;
;                         *(LAS f32x4*)(lds + r * 1024 + ((c16 ^ (r & 15)) << 4)) = acc[0][bj][m][n]; }
;         asm volatile("s_waitcnt vmcnt(0)" ::: "memory");
;         if (wid < 4 && lane == 0) __hip_atomic_fetch_add(cnt + 64 * u.pm, 1u, __ATOMIC_RELAXED, __HIP_MEMORY_SCOPE_AGENT);
	v_mul_f32_e32 v134, v33, v33
	v_fmac_f32_e32 v3, v30, v30
	v_fmac_f32_e32 v134, v32, v32
	v_add_f32_e32 v3, v3, v134
	v_add_f32_e32 v2, v3, v2
	v_mul_f32_e32 v3, v23, v23
	v_mul_f32_e32 v134, v25, v25
	v_fmac_f32_e32 v3, v22, v22
	v_fmac_f32_e32 v134, v24, v24
	v_add_f32_e32 v3, v3, v134
	v_add_f32_e32 v2, v3, v2
	v_mov_b32_e32 v3, v2
	s_nop 1
	v_permlane16_swap_b32_e32 v2, v3
	v_add_f32_e32 v2, v2, v3
	v_mov_b32_e32 v3, v2
	s_nop 1
	v_permlane32_swap_b32_e32 v2, v3
	s_and_saveexec_b64 s[12:13], s[38:39]
	s_lshl_b32 s7, s52, 10
	s_add_i32 s7, s5, s7
	v_add_f32_e32 v2, v2, v3
	v_lshl_add_u32 v3, v168, 4, s7
	ds_write_b32 v3, v2 offset:2304
	s_or_b64 exec, exec, s[12:13]
	v_mul_f32_e32 v2, v51, v51
	v_mul_f32_e32 v3, v53, v53
	v_fmac_f32_e32 v2, v50, v50
	v_fmac_f32_e32 v3, v52, v52
	v_add_f32_e32 v2, v2, v3
	v_mul_f32_e32 v3, v43, v43
	v_mul_f32_e32 v134, v45, v45
	v_fmac_f32_e32 v3, v42, v42
	v_fmac_f32_e32 v134, v44, v44
	v_add_f32_e32 v3, v3, v134
	v_add_f32_e32 v2, v3, v2
	v_mul_f32_e32 v3, v19, v19
	v_mul_f32_e32 v134, v21, v21
	v_fmac_f32_e32 v3, v18, v18
	v_fmac_f32_e32 v134, v20, v20
	v_add_f32_e32 v3, v3, v134
	v_add_f32_e32 v2, v3, v2
	v_mul_f32_e32 v3, v15, v15
	v_mul_f32_e32 v134, v17, v17
	v_fmac_f32_e32 v3, v14, v14
	v_fmac_f32_e32 v134, v16, v16
	v_add_f32_e32 v3, v3, v134
	v_add_f32_e32 v2, v3, v2
	v_mov_b32_e32 v3, v2
	s_nop 1
	v_permlane16_swap_b32_e32 v2, v3
	v_add_f32_e32 v2, v2, v3
	v_mov_b32_e32 v3, v2
	s_nop 1
	v_permlane32_swap_b32_e32 v2, v3
	s_and_saveexec_b64 s[12:13], s[38:39]
	s_lshl_b32 s7, s52, 10
	s_add_i32 s7, s5, s7
	v_add_f32_e32 v2, v2, v3
	v_lshl_add_u32 v3, v168, 4, s7
	ds_write_b32 v3, v2 offset:2560
	s_or_b64 exec, exec, s[12:13]
	v_mul_f32_e32 v2, v35, v35
	v_mul_f32_e32 v3, v37, v37
	v_fmac_f32_e32 v2, v34, v34
	v_fmac_f32_e32 v3, v36, v36
	v_add_f32_e32 v2, v2, v3
	v_mul_f32_e32 v3, v27, v27
	v_mul_f32_e32 v134, v29, v29
	v_fmac_f32_e32 v3, v26, v26
	v_fmac_f32_e32 v134, v28, v28
	v_add_f32_e32 v3, v3, v134
	v_add_f32_e32 v2, v3, v2
	v_mul_f32_e32 v3, v11, v11
	v_mul_f32_e32 v134, v13, v13
	v_fmac_f32_e32 v3, v10, v10
	v_fmac_f32_e32 v134, v12, v12
	v_add_f32_e32 v3, v3, v134
	v_add_f32_e32 v2, v3, v2
	v_mul_f32_e32 v3, v7, v7
	v_mul_f32_e32 v134, v9, v9
	v_fmac_f32_e32 v3, v6, v6
	v_fmac_f32_e32 v134, v8, v8
	v_add_f32_e32 v3, v3, v134
	v_add_f32_e32 v2, v3, v2
	v_mov_b32_e32 v3, v2
	s_nop 1
	v_permlane16_swap_b32_e32 v2, v3
	v_add_f32_e32 v2, v2, v3
	v_mov_b32_e32 v3, v2
	s_nop 1
	v_permlane32_swap_b32_e32 v2, v3
	s_and_saveexec_b64 s[12:13], s[38:39]
	s_lshl_b32 s7, s52, 10
	s_add_i32 s5, s5, s7
	v_add_f32_e32 v2, v2, v3
	v_lshl_add_u32 v3, v168, 4, s5
	ds_write_b32 v3, v2 offset:2816
	s_or_b64 exec, exec, s[12:13]
	s_and_b32 s5, s51, 0xffffffc0
	v_or_b32_e32 v134, s5, v216
	v_readlane_b32 s5, v254, 58
	s_lshr_b32 s101, s5, 18
	s_add_i32 s101, s101, 1
	s_add_u32 s5, s8, s5
	s_addc_u32 s7, s9, 0
	s_waitcnt lgkmcnt(0)
	s_barrier
	s_add_u32 s14, s5, 0xc00000
	s_movk_i32 s5, 0x100
	s_addc_u32 s15, s7, 0
	v_cmp_gt_i32_e64 s[42:43], s5, v134
	s_and_saveexec_b64 s[12:13], s[42:43]
	s_cbranch_execz .LBB0_1051
	v_lshl_add_u32 v2, v134, 4, 0
	v_add_u32_e32 v2, 0x20400, v2
	ds_read_b128 v[136:139], v2
	s_ashr_i32 s7, s6, 31
	s_waitcnt lgkmcnt(0)
	v_mov_b32_e32 v2, v137
	v_mov_b32_e32 v3, v138
	v_mov_b32_e32 v137, v139
	v_pk_add_f32 v[2:3], v[2:3], v[136:137]
	v_lshl_add_u32 v136, s53, 8, v134
	v_pk_add_f32 v[2:3], v[2:3], v[2:3] op_sel:[0,1] op_sel_hi:[1,0]
	v_lshlrev_b32_e32 v136, 6, v136
	s_lshl_b32 s100, s6, 3
	v_add_u32_e32 v136, s100, v136
	v_add_u32_e32 v136, 0x40000, v136
	v_mov_b32_e32 v3, s101
	global_store_dwordx2 v136, v[2:3], s[8:9] sc1
.LBB0_1051:
	s_or_b64 exec, exec, s[12:13]
	v_readlane_b32 s12, v255, 2
	v_readlane_b32 s13, v255, 3
	s_add_u32 s5, s8, s12
	s_addc_u32 s7, s9, s13
	s_add_u32 s5, s5, 0x10000
	s_addc_u32 s7, s7, 0
	s_lshl_b32 s12, s54, 3
	s_lshl_b32 s13, s52, 16
	s_add_i32 s13, s13, 0
	v_or_b32_e32 v3, s12, v4
	v_bitop3_b32 v4, s12, v168, v4 bitop3:0x36
	v_lshl_add_u32 v2, v168, 10, s13
	v_lshlrev_b32_e32 v4, 4, v4
	v_add_u32_e32 v217, v2, v4
	v_bitop3_b32 v4, v3, v168, 4 bitop3:0x36
	v_lshlrev_b32_e32 v4, 4, v4
	v_add_u32_e32 v218, v2, v4
	v_bitop3_b32 v4, v3, v168, 32 bitop3:0x36
	v_bitop3_b32 v3, v3, v168, 36 bitop3:0x36
	v_lshlrev_b32_e32 v4, 4, v4
	v_lshlrev_b32_e32 v3, 4, v3
	v_add_u32_e32 v219, v2, v4
	v_add_u32_e32 v220, v2, v3
	ds_write_b128 v217, v[130:133]
	ds_write_b128 v218, v[126:129]
	ds_write_b128 v219, v[114:117]
	ds_write_b128 v220, v[102:105]
	ds_write_b128 v217, v[122:125] offset:16384
	ds_write_b128 v218, v[118:121] offset:16384
	ds_write_b128 v219, v[94:97] offset:16384
	ds_write_b128 v220, v[86:89] offset:16384
	ds_write_b128 v217, v[110:113] offset:32768
	ds_write_b128 v218, v[106:109] offset:32768
	ds_write_b128 v219, v[82:85] offset:32768
	ds_write_b128 v220, v[78:81] offset:32768
	ds_write_b128 v217, v[98:101] offset:49152
	ds_write_b128 v218, v[90:93] offset:49152
	ds_write_b128 v219, v[74:77] offset:49152
	ds_write_b128 v220, v[70:73] offset:49152
	v_cmp_eq_u32_e64 s[40:41], 0, v216
	s_and_saveexec_b64 s[16:17], s[42:43]
	s_cbranch_execz .Lmy_g2_nosweep
	v_lshl_add_u32 v118, s53, 8, v134
	v_lshlrev_b32_e32 v118, 6, v118
	v_add_u32_e32 v118, 0x40000, v118
	global_load_dwordx4 v[100:103], v118, s[8:9] sc1
	global_load_dwordx4 v[104:107], v118, s[8:9] offset:16 sc1
	global_load_dwordx4 v[108:111], v118, s[8:9] offset:32 sc1
	global_load_dwordx4 v[114:117], v118, s[8:9] offset:48 sc1
;     __device__ __forceinline__ HT hload(unsigned eoff) const { const u32x2 a = *(const u32x2*)((const char*)hi + eoff * 2u); const u32x2 b = *(const u32x2*)((const char*)lo + eoff * 2u); return (u32x4){a.x, a.y, b.x, b.y}; }
;     __device__ __forceinline__ void fused(f32x4 (&acc)[2][2][4][2], const Unit& u, int wr, int wc, int fr, int fq, LAS unsigned char* lds, int wid, int lane) const {
;     ...
;         if (wid < 4 && lane == 0) __hip_atomic_fetch_add(cnt + 64 * u.pm, 1u, __ATOMIC_RELAXED, __HIP_MEMORY_SCOPE_AGENT);
; #pragma unroll
;         for (int j = 0; j < 16; ++j) H[j] = hload(rbase + (unsigned)(j * D));
;         if (wid == 0) {
;             const unsigned long long t0 = __builtin_amdgcn_s_memrealtime();
;             for (;;) {
;                 if ((unsigned)__builtin_amdgcn_readfirstlane((int)__hip_atomic_load(cnt + 64 * u.pm, __ATOMIC_RELAXED, __HIP_MEMORY_SCOPE_AGENT)) >= 32u) break;
;                 if (__builtin_amdgcn_s_memrealtime() - t0 > 2000000ull) { if (lane == 0) __hip_atomic_store(tmo, 1u, __ATOMIC_RELAXED, __HIP_MEMORY_SCOPE_AGENT); break; }
;                 __builtin_amdgcn_s_sleep(2);
;             }
;             __builtin_amdgcn_fence(__ATOMIC_ACQUIRE, "agent");
;         }
;         asm volatile("s_waitcnt vmcnt(0) lgkmcnt(0)" ::: "memory"); __builtin_amdgcn_s_barrier(); asm volatile("" ::: "memory");
;         if (tid < 256) { const f32x4* sl = (const f32x4*)(xbuf + (size_t)(u.pm * BM + tid) * 8);
;             const f32x4 a = sl[0], b = sl[1]; const float t = ((a.x + a.y) + (a.z + a.w)) + ((b.x + b.y) + (b.z + b.w));
;             S[tid] = alpha * __builtin_amdgcn_rsqf(t * (1.0f / 2048.0f) + 1e-6f); }
.Lmy_g2_nosweep:
	s_or_b64 exec, exec, s[16:17]
	s_lshl_b32 s12, s53, 19
	s_lshl_b32 s13, s50, 15
	v_lshlrev_b32_e32 v98, 2, v216
	s_add_i32 s16, s12, s13
	v_or_b32_e32 v2, s4, v98
	s_add_u32 s12, s8, 0x9000000
	v_add_lshl_u32 v4, s16, v2, 1
	s_addc_u32 s13, s9, 0
	v_add_u32_e32 v96, 0x1000, v4
	v_add_u32_e32 v92, 0x5000, v4
	v_add_u32_e32 v86, 0x9000, v4
	v_add_u32_e32 v94, 0x2000, v4
	v_add_u32_e32 v90, 0x3000, v4
	v_add_u32_e32 v84, 0x4000, v4
	global_load_dwordx2 v[190:191], v96, s[12:13]
	global_load_dwordx2 v[188:189], v94, s[12:13]
	global_load_dwordx2 v[186:187], v90, s[12:13]
	global_load_dwordx2 v[176:177], v84, s[12:13]
	v_add_u32_e32 v88, 0x6000, v4
	v_add_u32_e32 v82, 0x7000, v4
	v_add_u32_e32 v76, 0x8000, v4
	global_load_dwordx2 v[174:175], v92, s[12:13]
	global_load_dwordx2 v[172:173], v88, s[12:13]
	global_load_dwordx2 v[170:171], v82, s[12:13]
	global_load_dwordx2 v[160:161], v76, s[12:13]
	v_add_u32_e32 v80, 0xa000, v4
	v_add_u32_e32 v74, 0xb000, v4
	v_add_u32_e32 v70, 0xc000, v4
	global_load_dwordx2 v[158:159], v86, s[12:13]
	global_load_dwordx2 v[156:157], v80, s[12:13]
	global_load_dwordx2 v[154:155], v74, s[12:13]
	global_load_dwordx2 v[144:145], v70, s[12:13]
	v_add_u32_e32 v78, 0xd000, v4
	v_add_u32_e32 v72, 0xe000, v4
	v_add_u32_e32 v2, 0xf000, v4
	global_load_dwordx2 v[194:195], v4, s[12:13]
	global_load_dwordx2 v[136:137], v78, s[12:13]
	global_load_dwordx2 v[124:125], v72, s[12:13]
	global_load_dwordx2 v[112:113], v2, s[12:13]
	v_mov_b32_e32 v97, v5
	v_mov_b32_e32 v95, v5
	v_mov_b32_e32 v91, v5
	v_mov_b32_e32 v85, v5
	v_mov_b32_e32 v93, v5
	v_mov_b32_e32 v89, v5
	v_mov_b32_e32 v83, v5
	v_mov_b32_e32 v77, v5
	v_mov_b32_e32 v87, v5
	v_mov_b32_e32 v81, v5
	v_mov_b32_e32 v75, v5
	v_mov_b32_e32 v71, v5
	v_mov_b32_e32 v79, v5
	v_mov_b32_e32 v73, v5
	v_mov_b32_e32 v3, v5
	v_lshl_add_u64 v[214:215], s[12:13], 0, v[4:5]
	v_lshl_add_u64 v[212:213], s[12:13], 0, v[96:97]
	v_lshl_add_u64 v[196:197], s[12:13], 0, v[94:95]
	v_lshl_add_u64 v[192:193], s[12:13], 0, v[90:91]
	v_lshl_add_u64 v[184:185], s[12:13], 0, v[84:85]
	v_lshl_add_u64 v[182:183], s[12:13], 0, v[92:93]
	v_lshl_add_u64 v[180:181], s[12:13], 0, v[88:89]
	v_lshl_add_u64 v[178:179], s[12:13], 0, v[82:83]
	v_lshl_add_u64 v[168:169], s[12:13], 0, v[76:77]
	v_lshl_add_u64 v[166:167], s[12:13], 0, v[86:87]
	v_lshl_add_u64 v[164:165], s[12:13], 0, v[80:81]
	v_lshl_add_u64 v[162:163], s[12:13], 0, v[74:75]
	v_lshl_add_u64 v[152:153], s[12:13], 0, v[70:71]
	v_lshl_add_u64 v[150:151], s[12:13], 0, v[78:79]
	v_lshl_add_u64 v[148:149], s[12:13], 0, v[72:73]
	v_lshl_add_u64 v[146:147], s[12:13], 0, v[2:3]
	s_lshl_b32 s7, s53, 8
	s_and_saveexec_b64 s[16:17], s[42:43]
	s_cbranch_execz .LBB0_1068
	s_waitcnt vmcnt(16)
	s_mov_b32 s22, 0
.Lmy_g2_chk:
	v_xor_b32_e32 v119, s101, v101
	v_xor_b32_e32 v120, s101, v103
	v_xor_b32_e32 v121, s101, v105
	v_or3_b32 v119, v119, v120, v121
	v_xor_b32_e32 v120, s101, v107
	v_xor_b32_e32 v121, s101, v109
	v_or3_b32 v119, v119, v120, v121
	v_xor_b32_e32 v120, s101, v111
	v_xor_b32_e32 v121, s101, v115
	v_or3_b32 v119, v119, v120, v121
	v_xor_b32_e32 v120, s101, v117
	v_or_b32_e32 v119, v119, v120
	v_cmp_ne_u32_e32 vcc, 0, v119
	s_cbranch_vccz .Lmy_g2_ok
	s_add_i32 s22, s22, 1
	s_cmpk_lt_u32 s22, 0x4000
	s_cbranch_scc0 .Lmy_g2_tmo
	s_sleep 1
	global_load_dwordx4 v[100:103], v118, s[8:9] sc1
	global_load_dwordx4 v[104:107], v118, s[8:9] offset:16 sc1
	global_load_dwordx4 v[108:111], v118, s[8:9] offset:32 sc1
	global_load_dwordx4 v[114:117], v118, s[8:9] offset:48 sc1
	s_waitcnt vmcnt(0)
	s_branch .Lmy_g2_chk
.Lmy_g2_tmo:
	global_store_dword v5, v232, s[8:9] sc1
.Lmy_g2_ok:
	v_add_f32_e32 v100, v100, v102
	v_add_f32_e32 v104, v104, v106
	v_add_f32_e32 v108, v108, v110
	v_add_f32_e32 v114, v114, v116
	v_add_f32_e32 v100, v100, v104
	v_add_f32_e32 v108, v108, v114
	v_add_f32_e32 v2, v100, v108
	v_fmamk_f32 v2, v2, 0x3a000000, v1
	v_rsq_f32_e32 v2, v2
	v_lshl_add_u32 v3, v134, 2, 0
	v_add_u32_e32 v3, 0x21400, v3
	ds_write_b32 v3, v2
